# s_setprio 1 for the later-dispatched block (bid>=256) inside the GEMM K-loops: balances co-resident blocks
# speedup vs baseline: 1.0403x; 1.0027x over previous
.LBB0_171:
	s_add_u32 s74, s74, s50
	s_addc_u32 s75, s75, s51
	s_add_u32 s72, s72, s60
	s_addc_u32 s73, s73, s61
	v_mov_b32_e32 v128, 0
	v_mov_b32_e32 v129, 0
	v_mov_b32_e32 v130, 0
	v_mov_b32_e32 v131, 0
	v_mov_b32_e32 v132, 0
	v_mov_b32_e32 v133, 0
	v_mov_b32_e32 v134, 0
	v_mov_b32_e32 v135, 0
	v_mov_b32_e32 v136, 0
	v_mov_b32_e32 v137, 0
	v_mov_b32_e32 v138, 0
	v_mov_b32_e32 v139, 0
	v_mov_b32_e32 v140, 0
	v_mov_b32_e32 v141, 0
	v_mov_b32_e32 v142, 0
	v_mov_b32_e32 v143, 0
	v_mov_b32_e32 v144, 0
	v_mov_b32_e32 v145, 0
	v_mov_b32_e32 v146, 0
	v_mov_b32_e32 v147, 0
	v_mov_b32_e32 v148, 0
	v_mov_b32_e32 v149, 0
	v_mov_b32_e32 v150, 0
	v_mov_b32_e32 v151, 0
	v_readlane_b32 s100, v255, 24
	s_nop 1
	s_bitcmp1_b32 s100, 8
	s_cbranch_scc0 .Lgemm_g1_noyp
	s_setprio 1
.Lgemm_g1_noyp:
.Lgemm_g1_main:
	s_add_i32 s18, s11, 0
	v_add_u32_e32 v182, s18, v178
	v_add_u32_e32 v152, v182, v180
	ds_read_b128 v[172:175], v152
	ds_read_b128 v[168:171], v152 offset:2048
	ds_read_b128 v[156:159], v152 offset:4096
	ds_read_b128 v[152:155], v152 offset:6144
	v_add_u32_e32 v183, s18, v179
	v_add_u32_e32 v160, v183, v180
	ds_read_b128 v[164:167], v160 offset:16384
	ds_read_b128 v[160:163], v160 offset:18432
	s_add_i32 s18, s0, s10
	s_mov_b32 m0, s18
	v_mfma_f32_32x32x16_bf16 v[112:127], v[136:139], v[148:151], v[112:127]
	global_load_lds_dwordx4 v176, s[74:75]
	v_mfma_f32_32x32x16_bf16 v[96:111], v[132:135], v[148:151], v[96:111]
	v_mfma_f32_32x32x16_bf16 v[80:95], v[136:139], v[144:147], v[80:95]
	s_add_i32 m0, s18, 0x1000
	s_add_u32 s98, s74, 0x1000
	s_addc_u32 s99, s75, 0
	v_mfma_f32_32x32x16_bf16 v[64:79], v[132:135], v[144:147], v[64:79]
	global_load_lds_dwordx4 v176, s[98:99]
	v_mfma_f32_32x32x16_bf16 v[48:63], v[136:139], v[140:143], v[48:63]
	s_add_i32 m0, s18, 0x2000
	s_add_u32 s98, s74, 0x2000
	s_addc_u32 s99, s75, 0
	v_mfma_f32_32x32x16_bf16 v[32:47], v[132:135], v[140:143], v[32:47]
	global_load_lds_dwordx4 v176, s[98:99]
	v_mfma_f32_32x32x16_bf16 v[16:31], v[136:139], v[128:131], v[16:31]
	v_mfma_f32_32x32x16_bf16 v[0:15], v[132:135], v[128:131], v[0:15]
	v_add_u32_e32 v128, v182, v181
	ds_read_b128 v[148:151], v128
	ds_read_b128 v[144:147], v128 offset:2048
	ds_read_b128 v[140:143], v128 offset:4096
	ds_read_b128 v[128:131], v128 offset:6144
	v_add_u32_e32 v132, v183, v181
	ds_read_b128 v[136:139], v132 offset:16384
	ds_read_b128 v[132:135], v132 offset:18432
	s_waitcnt lgkmcnt(6)
	s_add_i32 m0, s18, 0x3000
	s_add_u32 s98, s74, 0x3000
	s_addc_u32 s99, s75, 0
	v_mfma_f32_32x32x16_bf16 v[112:127], v[164:167], v[172:175], v[112:127]
	global_load_lds_dwordx4 v176, s[98:99]
	v_mfma_f32_32x32x16_bf16 v[96:111], v[160:163], v[172:175], v[96:111]
	v_mfma_f32_32x32x16_bf16 v[80:95], v[164:167], v[168:171], v[80:95]
	s_add_i32 m0, s18, 0x4000
	v_mfma_f32_32x32x16_bf16 v[64:79], v[160:163], v[168:171], v[64:79]
	global_load_lds_dwordx4 v176, s[72:73]
	v_mfma_f32_32x32x16_bf16 v[48:63], v[164:167], v[156:159], v[48:63]
	s_add_i32 m0, s18, 0x5000
	s_add_u32 s98, s72, 0x1000
	s_addc_u32 s99, s73, 0
	v_mfma_f32_32x32x16_bf16 v[32:47], v[160:163], v[156:159], v[32:47]
	global_load_lds_dwordx4 v176, s[98:99]
	v_mfma_f32_32x32x16_bf16 v[16:31], v[164:167], v[152:155], v[16:31]
	v_mfma_f32_32x32x16_bf16 v[0:15], v[160:163], v[152:155], v[0:15]
	s_add_u32 s74, s74, 0x80000
	s_addc_u32 s75, s75, 0
	s_add_u32 s72, s72, 0x5e000
	s_addc_u32 s73, s73, 0
	s_add_i32 s18, s10, 0x6000
	s_cmpk_lg_u32 s10, 0xc000
	s_cselect_b32 s10, s18, 0
	s_add_i32 s18, s11, 0x6000
	s_cmpk_lg_u32 s11, 0xc000
	s_cselect_b32 s11, s18, 0
	s_add_i32 s1, s1, 1
	s_waitcnt vmcnt(6) lgkmcnt(0)
	s_barrier
	s_cmp_lg_u32 s1, 62
	s_cbranch_scc1 .Lgemm_g1_main
.Lgemm_g1_tail:
	s_setprio 0
	s_add_i32 s18, s11, 0
	v_add_u32_e32 v182, s18, v178
	v_add_u32_e32 v152, v182, v180
	ds_read_b128 v[172:175], v152
	ds_read_b128 v[168:171], v152 offset:2048
	ds_read_b128 v[156:159], v152 offset:4096
	ds_read_b128 v[152:155], v152 offset:6144
	v_add_u32_e32 v183, s18, v179
	v_add_u32_e32 v160, v183, v180
	ds_read_b128 v[164:167], v160 offset:16384
	ds_read_b128 v[160:163], v160 offset:18432
	v_mfma_f32_32x32x16_bf16 v[112:127], v[136:139], v[148:151], v[112:127]
	v_mfma_f32_32x32x16_bf16 v[96:111], v[132:135], v[148:151], v[96:111]
	v_mfma_f32_32x32x16_bf16 v[80:95], v[136:139], v[144:147], v[80:95]
	v_mfma_f32_32x32x16_bf16 v[64:79], v[132:135], v[144:147], v[64:79]
	v_mfma_f32_32x32x16_bf16 v[48:63], v[136:139], v[140:143], v[48:63]
	v_mfma_f32_32x32x16_bf16 v[32:47], v[132:135], v[140:143], v[32:47]
	v_mfma_f32_32x32x16_bf16 v[16:31], v[136:139], v[128:131], v[16:31]
	v_mfma_f32_32x32x16_bf16 v[0:15], v[132:135], v[128:131], v[0:15]
	v_add_u32_e32 v128, v182, v181
	ds_read_b128 v[148:151], v128
	ds_read_b128 v[144:147], v128 offset:2048
	ds_read_b128 v[140:143], v128 offset:4096
	ds_read_b128 v[128:131], v128 offset:6144
	v_add_u32_e32 v132, v183, v181
	ds_read_b128 v[136:139], v132 offset:16384
	ds_read_b128 v[132:135], v132 offset:18432
	s_waitcnt lgkmcnt(6)
	v_mfma_f32_32x32x16_bf16 v[112:127], v[164:167], v[172:175], v[112:127]
	v_mfma_f32_32x32x16_bf16 v[96:111], v[160:163], v[172:175], v[96:111]
	v_mfma_f32_32x32x16_bf16 v[80:95], v[164:167], v[168:171], v[80:95]
	v_mfma_f32_32x32x16_bf16 v[64:79], v[160:163], v[168:171], v[64:79]
	v_mfma_f32_32x32x16_bf16 v[48:63], v[164:167], v[156:159], v[48:63]
	v_mfma_f32_32x32x16_bf16 v[32:47], v[160:163], v[156:159], v[32:47]
	v_mfma_f32_32x32x16_bf16 v[16:31], v[164:167], v[152:155], v[16:31]
	v_mfma_f32_32x32x16_bf16 v[0:15], v[160:163], v[152:155], v[0:15]
	s_add_i32 s18, s11, 0x6000
	s_cmpk_lg_u32 s11, 0xc000
	s_cselect_b32 s11, s18, 0
	s_add_i32 s1, s1, 1
	s_waitcnt vmcnt(0) lgkmcnt(0)
	s_barrier
	s_cmp_lg_u32 s1, 64
	s_cbranch_scc1 .Lgemm_g1_tail
	s_branch .LBB0_179

.LBB0_224:
	s_add_u32 s68, s68, s50
	s_addc_u32 s69, s69, s51
	s_add_u32 s70, s70, s60
	s_addc_u32 s71, s71, s61
	v_mov_b32_e32 v128, 0
	v_mov_b32_e32 v129, 0
	v_mov_b32_e32 v130, 0
	v_mov_b32_e32 v131, 0
	v_mov_b32_e32 v132, 0
	v_mov_b32_e32 v133, 0
	v_mov_b32_e32 v134, 0
	v_mov_b32_e32 v135, 0
	v_mov_b32_e32 v136, 0
	v_mov_b32_e32 v137, 0
	v_mov_b32_e32 v138, 0
	v_mov_b32_e32 v139, 0
	v_mov_b32_e32 v140, 0
	v_mov_b32_e32 v141, 0
	v_mov_b32_e32 v142, 0
	v_mov_b32_e32 v143, 0
	v_mov_b32_e32 v144, 0
	v_mov_b32_e32 v145, 0
	v_mov_b32_e32 v146, 0
	v_mov_b32_e32 v147, 0
	v_mov_b32_e32 v148, 0
	v_mov_b32_e32 v149, 0
	v_mov_b32_e32 v150, 0
	v_mov_b32_e32 v151, 0
	v_readlane_b32 s100, v255, 24
	s_nop 1
	s_bitcmp1_b32 s100, 8
	s_cbranch_scc0 .Lgemm_g2_noyp
	s_setprio 1
.Lgemm_g2_noyp:
.Lgemm_g2_main:
	s_add_i32 s18, s11, 0
	v_add_u32_e32 v182, s18, v178
	v_add_u32_e32 v152, v182, v180
	ds_read_b128 v[172:175], v152
	ds_read_b128 v[168:171], v152 offset:2048
	ds_read_b128 v[156:159], v152 offset:4096
	ds_read_b128 v[152:155], v152 offset:6144
	v_add_u32_e32 v183, s18, v179
	v_add_u32_e32 v160, v183, v180
	ds_read_b128 v[164:167], v160 offset:16384
	ds_read_b128 v[160:163], v160 offset:18432
	s_add_i32 s18, s0, s10
	s_mov_b32 m0, s18
	v_mfma_f32_32x32x16_bf16 v[112:127], v[148:151], v[132:135], v[112:127]
	global_load_lds_dwordx4 v176, s[68:69]
	v_mfma_f32_32x32x16_bf16 v[96:111], v[148:151], v[136:139], v[96:111]
	v_mfma_f32_32x32x16_bf16 v[80:95], v[144:147], v[132:135], v[80:95]
	s_add_i32 m0, s18, 0x1000
	s_add_u32 s98, s68, 0x1000
	s_addc_u32 s99, s69, 0
	v_mfma_f32_32x32x16_bf16 v[64:79], v[144:147], v[136:139], v[64:79]
	global_load_lds_dwordx4 v176, s[98:99]
	v_mfma_f32_32x32x16_bf16 v[48:63], v[140:143], v[132:135], v[48:63]
	s_add_i32 m0, s18, 0x2000
	s_add_u32 s98, s68, 0x2000
	s_addc_u32 s99, s69, 0
	v_mfma_f32_32x32x16_bf16 v[32:47], v[140:143], v[136:139], v[32:47]
	global_load_lds_dwordx4 v176, s[98:99]
	v_mfma_f32_32x32x16_bf16 v[16:31], v[128:131], v[132:135], v[16:31]
	v_mfma_f32_32x32x16_bf16 v[0:15], v[128:131], v[136:139], v[0:15]
	v_add_u32_e32 v128, v182, v181
	ds_read_b128 v[148:151], v128
	ds_read_b128 v[144:147], v128 offset:2048
	ds_read_b128 v[140:143], v128 offset:4096
	ds_read_b128 v[128:131], v128 offset:6144
	v_add_u32_e32 v136, v183, v181
	ds_read_b128 v[132:135], v136 offset:16384
	ds_read_b128 v[136:139], v136 offset:18432
	s_waitcnt lgkmcnt(6)
	s_add_i32 m0, s18, 0x3000
	s_add_u32 s98, s68, 0x3000
	s_addc_u32 s99, s69, 0
	v_mfma_f32_32x32x16_bf16 v[112:127], v[172:175], v[164:167], v[112:127]
	global_load_lds_dwordx4 v176, s[98:99]
	v_mfma_f32_32x32x16_bf16 v[96:111], v[172:175], v[160:163], v[96:111]
	v_mfma_f32_32x32x16_bf16 v[80:95], v[168:171], v[164:167], v[80:95]
	s_add_i32 m0, s18, 0x4000
	v_mfma_f32_32x32x16_bf16 v[64:79], v[168:171], v[160:163], v[64:79]
	global_load_lds_dwordx4 v176, s[70:71]
	v_mfma_f32_32x32x16_bf16 v[48:63], v[156:159], v[164:167], v[48:63]
	s_add_i32 m0, s18, 0x5000
	s_add_u32 s98, s70, 0x1000
	s_addc_u32 s99, s71, 0
	v_mfma_f32_32x32x16_bf16 v[32:47], v[156:159], v[160:163], v[32:47]
	global_load_lds_dwordx4 v176, s[98:99]
	v_mfma_f32_32x32x16_bf16 v[16:31], v[152:155], v[164:167], v[16:31]
	v_mfma_f32_32x32x16_bf16 v[0:15], v[152:155], v[160:163], v[0:15]
	s_add_u32 s68, s68, 0x80000
	s_addc_u32 s69, s69, 0
	s_add_u32 s70, s70, 0x5e000
	s_addc_u32 s71, s71, 0
	s_add_i32 s18, s10, 0x6000
	s_cmpk_lg_u32 s10, 0xc000
	s_cselect_b32 s10, s18, 0
	s_add_i32 s18, s11, 0x6000
	s_cmpk_lg_u32 s11, 0xc000
	s_cselect_b32 s11, s18, 0
	s_add_i32 s1, s1, 1
	s_waitcnt vmcnt(6) lgkmcnt(0)
	s_barrier
	s_cmp_lg_u32 s1, 62
	s_cbranch_scc1 .Lgemm_g2_main
.Lgemm_g2_tail:
	s_setprio 0
	s_add_i32 s18, s11, 0
	v_add_u32_e32 v182, s18, v178
	v_add_u32_e32 v152, v182, v180
	ds_read_b128 v[172:175], v152
	ds_read_b128 v[168:171], v152 offset:2048
	ds_read_b128 v[156:159], v152 offset:4096
	ds_read_b128 v[152:155], v152 offset:6144
	v_add_u32_e32 v183, s18, v179
	v_add_u32_e32 v160, v183, v180
	ds_read_b128 v[164:167], v160 offset:16384
	ds_read_b128 v[160:163], v160 offset:18432
	v_mfma_f32_32x32x16_bf16 v[112:127], v[148:151], v[132:135], v[112:127]
	v_mfma_f32_32x32x16_bf16 v[96:111], v[148:151], v[136:139], v[96:111]
	v_mfma_f32_32x32x16_bf16 v[80:95], v[144:147], v[132:135], v[80:95]
	v_mfma_f32_32x32x16_bf16 v[64:79], v[144:147], v[136:139], v[64:79]
	v_mfma_f32_32x32x16_bf16 v[48:63], v[140:143], v[132:135], v[48:63]
	v_mfma_f32_32x32x16_bf16 v[32:47], v[140:143], v[136:139], v[32:47]
	v_mfma_f32_32x32x16_bf16 v[16:31], v[128:131], v[132:135], v[16:31]
	v_mfma_f32_32x32x16_bf16 v[0:15], v[128:131], v[136:139], v[0:15]
	v_add_u32_e32 v128, v182, v181
	ds_read_b128 v[148:151], v128
	ds_read_b128 v[144:147], v128 offset:2048
	ds_read_b128 v[140:143], v128 offset:4096
	ds_read_b128 v[128:131], v128 offset:6144
	v_add_u32_e32 v136, v183, v181
	ds_read_b128 v[132:135], v136 offset:16384
	ds_read_b128 v[136:139], v136 offset:18432
	s_waitcnt lgkmcnt(6)
	v_mfma_f32_32x32x16_bf16 v[112:127], v[172:175], v[164:167], v[112:127]
	v_mfma_f32_32x32x16_bf16 v[96:111], v[172:175], v[160:163], v[96:111]
	v_mfma_f32_32x32x16_bf16 v[80:95], v[168:171], v[164:167], v[80:95]
	v_mfma_f32_32x32x16_bf16 v[64:79], v[168:171], v[160:163], v[64:79]
	v_mfma_f32_32x32x16_bf16 v[48:63], v[156:159], v[164:167], v[48:63]
	v_mfma_f32_32x32x16_bf16 v[32:47], v[156:159], v[160:163], v[32:47]
	v_mfma_f32_32x32x16_bf16 v[16:31], v[152:155], v[164:167], v[16:31]
	v_mfma_f32_32x32x16_bf16 v[0:15], v[152:155], v[160:163], v[0:15]
	s_add_i32 s18, s11, 0x6000
	s_cmpk_lg_u32 s11, 0xc000
	s_cselect_b32 s11, s18, 0
	s_add_i32 s1, s1, 1
	s_waitcnt vmcnt(0) lgkmcnt(0)
	s_barrier
	s_cmp_lg_u32 s1, 64
	s_cbranch_scc1 .Lgemm_g2_tail
	s_branch .LBB0_165

.LBB0_291:
	s_add_u32 s6, s6, s56
	s_addc_u32 s7, s7, s57
	s_add_u32 s4, s4, s64
	s_addc_u32 s5, s5, s65
	v_mov_b32_e32 v128, 0
	v_mov_b32_e32 v129, 0
	v_mov_b32_e32 v130, 0
	v_mov_b32_e32 v131, 0
	v_mov_b32_e32 v132, 0
	v_mov_b32_e32 v133, 0
	v_mov_b32_e32 v134, 0
	v_mov_b32_e32 v135, 0
	v_mov_b32_e32 v136, 0
	v_mov_b32_e32 v137, 0
	v_mov_b32_e32 v138, 0
	v_mov_b32_e32 v139, 0
	v_mov_b32_e32 v140, 0
	v_mov_b32_e32 v141, 0
	v_mov_b32_e32 v142, 0
	v_mov_b32_e32 v143, 0
	v_mov_b32_e32 v144, 0
	v_mov_b32_e32 v145, 0
	v_mov_b32_e32 v146, 0
	v_mov_b32_e32 v147, 0
	v_mov_b32_e32 v148, 0
	v_mov_b32_e32 v149, 0
	v_mov_b32_e32 v150, 0
	v_mov_b32_e32 v151, 0
	v_readlane_b32 s100, v255, 24
	s_nop 1
	s_bitcmp1_b32 s100, 8
	s_cbranch_scc0 .Lgemm_g3_noyp
	s_setprio 1
.Lgemm_g3_noyp:
.Lgemm_g3_main:
	s_add_i32 s79, s37, 0
	v_add_u32_e32 v182, s79, v178
	v_add_u32_e32 v152, v182, v180
	ds_read_b128 v[172:175], v152
	ds_read_b128 v[168:171], v152 offset:2048
	ds_read_b128 v[156:159], v152 offset:4096
	ds_read_b128 v[152:155], v152 offset:6144
	v_add_u32_e32 v183, s79, v179
	v_add_u32_e32 v160, v183, v180
	ds_read_b128 v[164:167], v160 offset:16384
	ds_read_b128 v[160:163], v160 offset:18432
	s_add_i32 s8, s22, s36
	s_mov_b32 m0, s8
	v_mfma_f32_32x32x16_bf16 v[112:127], v[148:151], v[132:135], v[112:127]
	global_load_lds_dwordx4 v176, s[6:7]
	v_mfma_f32_32x32x16_bf16 v[96:111], v[148:151], v[136:139], v[96:111]
	v_mfma_f32_32x32x16_bf16 v[80:95], v[144:147], v[132:135], v[80:95]
	s_add_i32 m0, s8, 0x1000
	s_add_u32 s98, s6, 0x1000
	s_addc_u32 s99, s7, 0
	v_mfma_f32_32x32x16_bf16 v[64:79], v[144:147], v[136:139], v[64:79]
	global_load_lds_dwordx4 v176, s[98:99]
	v_mfma_f32_32x32x16_bf16 v[48:63], v[140:143], v[132:135], v[48:63]
	s_add_i32 m0, s8, 0x2000
	s_add_u32 s98, s6, 0x2000
	s_addc_u32 s99, s7, 0
	v_mfma_f32_32x32x16_bf16 v[32:47], v[140:143], v[136:139], v[32:47]
	global_load_lds_dwordx4 v176, s[98:99]
	v_mfma_f32_32x32x16_bf16 v[16:31], v[128:131], v[132:135], v[16:31]
	v_mfma_f32_32x32x16_bf16 v[0:15], v[128:131], v[136:139], v[0:15]
	v_add_u32_e32 v128, v182, v181
	ds_read_b128 v[148:151], v128
	ds_read_b128 v[144:147], v128 offset:2048
	ds_read_b128 v[140:143], v128 offset:4096
	ds_read_b128 v[128:131], v128 offset:6144
	v_add_u32_e32 v136, v183, v181
	ds_read_b128 v[132:135], v136 offset:16384
	ds_read_b128 v[136:139], v136 offset:18432
	s_waitcnt lgkmcnt(6)
	s_add_i32 m0, s8, 0x3000
	s_add_u32 s98, s6, 0x3000
	s_addc_u32 s99, s7, 0
	v_mfma_f32_32x32x16_bf16 v[112:127], v[172:175], v[164:167], v[112:127]
	global_load_lds_dwordx4 v176, s[98:99]
	v_mfma_f32_32x32x16_bf16 v[96:111], v[172:175], v[160:163], v[96:111]
	v_mfma_f32_32x32x16_bf16 v[80:95], v[168:171], v[164:167], v[80:95]
	s_add_i32 m0, s8, 0x4000
	v_mfma_f32_32x32x16_bf16 v[64:79], v[168:171], v[160:163], v[64:79]
	global_load_lds_dwordx4 v176, s[4:5]
	v_mfma_f32_32x32x16_bf16 v[48:63], v[156:159], v[164:167], v[48:63]
	s_add_i32 m0, s8, 0x5000
	s_add_u32 s98, s4, 0x1000
	s_addc_u32 s99, s5, 0
	v_mfma_f32_32x32x16_bf16 v[32:47], v[156:159], v[160:163], v[32:47]
	global_load_lds_dwordx4 v176, s[98:99]
	v_mfma_f32_32x32x16_bf16 v[16:31], v[152:155], v[164:167], v[16:31]
	v_mfma_f32_32x32x16_bf16 v[0:15], v[152:155], v[160:163], v[0:15]
	s_add_u32 s6, s6, 0x80000
	s_addc_u32 s7, s7, 0
	s_add_u32 s4, s4, 0x20000
	s_addc_u32 s5, s5, 0
	s_add_i32 s8, s36, 0x6000
	s_cmpk_lg_u32 s36, 0xc000
	s_cselect_b32 s36, s8, 0
	s_add_i32 s8, s37, 0x6000
	s_cmpk_lg_u32 s37, 0xc000
	s_cselect_b32 s37, s8, 0
	s_add_i32 s33, s33, 1
	s_waitcnt vmcnt(6) lgkmcnt(0)
	s_barrier
	s_cmp_lg_u32 s33, 6
	s_cbranch_scc1 .Lgemm_g3_main
.Lgemm_g3_tail:
	s_setprio 0
	s_add_i32 s79, s37, 0
	v_add_u32_e32 v182, s79, v178
	v_add_u32_e32 v152, v182, v180
	ds_read_b128 v[172:175], v152
	ds_read_b128 v[168:171], v152 offset:2048
	ds_read_b128 v[156:159], v152 offset:4096
	ds_read_b128 v[152:155], v152 offset:6144
	v_add_u32_e32 v183, s79, v179
	v_add_u32_e32 v160, v183, v180
	ds_read_b128 v[164:167], v160 offset:16384
	ds_read_b128 v[160:163], v160 offset:18432
	v_mfma_f32_32x32x16_bf16 v[112:127], v[148:151], v[132:135], v[112:127]
	v_mfma_f32_32x32x16_bf16 v[96:111], v[148:151], v[136:139], v[96:111]
	v_mfma_f32_32x32x16_bf16 v[80:95], v[144:147], v[132:135], v[80:95]
	v_mfma_f32_32x32x16_bf16 v[64:79], v[144:147], v[136:139], v[64:79]
	v_mfma_f32_32x32x16_bf16 v[48:63], v[140:143], v[132:135], v[48:63]
	v_mfma_f32_32x32x16_bf16 v[32:47], v[140:143], v[136:139], v[32:47]
	v_mfma_f32_32x32x16_bf16 v[16:31], v[128:131], v[132:135], v[16:31]
	v_mfma_f32_32x32x16_bf16 v[0:15], v[128:131], v[136:139], v[0:15]
	v_add_u32_e32 v128, v182, v181
	ds_read_b128 v[148:151], v128
	ds_read_b128 v[144:147], v128 offset:2048
	ds_read_b128 v[140:143], v128 offset:4096
	ds_read_b128 v[128:131], v128 offset:6144
	v_add_u32_e32 v136, v183, v181
	ds_read_b128 v[132:135], v136 offset:16384
	ds_read_b128 v[136:139], v136 offset:18432
	s_waitcnt lgkmcnt(6)
	v_mfma_f32_32x32x16_bf16 v[112:127], v[172:175], v[164:167], v[112:127]
	v_mfma_f32_32x32x16_bf16 v[96:111], v[172:175], v[160:163], v[96:111]
	v_mfma_f32_32x32x16_bf16 v[80:95], v[168:171], v[164:167], v[80:95]
	v_mfma_f32_32x32x16_bf16 v[64:79], v[168:171], v[160:163], v[64:79]
	v_mfma_f32_32x32x16_bf16 v[48:63], v[156:159], v[164:167], v[48:63]
	v_mfma_f32_32x32x16_bf16 v[32:47], v[156:159], v[160:163], v[32:47]
	v_mfma_f32_32x32x16_bf16 v[16:31], v[152:155], v[164:167], v[16:31]
	v_mfma_f32_32x32x16_bf16 v[0:15], v[152:155], v[160:163], v[0:15]
	s_add_i32 s8, s37, 0x6000
	s_cmpk_lg_u32 s37, 0xc000
	s_cselect_b32 s37, s8, 0
	s_add_i32 s33, s33, 1
	s_waitcnt vmcnt(0) lgkmcnt(0)
	s_barrier
	s_cmp_lg_u32 s33, 8
	s_cbranch_scc1 .Lgemm_g3_tail
	s_branch .LBB0_299

.Lgemm_g4_noyp:
.Lgemm_g4_main:
	s_add_i32 s33, s22, 0
	v_add_u32_e32 v182, s33, v178
	v_add_u32_e32 v152, v182, v180
	ds_read_b128 v[172:175], v152
	ds_read_b128 v[168:171], v152 offset:2048
	ds_read_b128 v[156:159], v152 offset:4096
	ds_read_b128 v[152:155], v152 offset:6144
	v_add_u32_e32 v183, s33, v179
	v_add_u32_e32 v160, v183, v180
	ds_read_b128 v[164:167], v160 offset:16384
	ds_read_b128 v[160:163], v160 offset:18432
	s_add_i32 s8, s0, s11
	s_mov_b32 m0, s8
	v_mfma_f32_32x32x16_bf16 v[112:127], v[144:147], v[148:151], v[112:127]
	global_load_lds_dwordx4 v176, s[6:7]
	v_mfma_f32_32x32x16_bf16 v[96:111], v[132:135], v[148:151], v[96:111]
	v_mfma_f32_32x32x16_bf16 v[80:95], v[144:147], v[140:143], v[80:95]
	s_add_i32 m0, s8, 0x1000
	s_add_u32 s98, s6, 0x1000
	s_addc_u32 s99, s7, 0
	v_mfma_f32_32x32x16_bf16 v[64:79], v[132:135], v[140:143], v[64:79]
	global_load_lds_dwordx4 v176, s[98:99]
	v_mfma_f32_32x32x16_bf16 v[48:63], v[144:147], v[136:139], v[48:63]
	s_add_i32 m0, s8, 0x2000
	s_add_u32 s98, s6, 0x2000
	s_addc_u32 s99, s7, 0
	v_mfma_f32_32x32x16_bf16 v[32:47], v[132:135], v[136:139], v[32:47]
	global_load_lds_dwordx4 v176, s[98:99]
	v_mfma_f32_32x32x16_bf16 v[16:31], v[144:147], v[128:131], v[16:31]
	v_mfma_f32_32x32x16_bf16 v[0:15], v[132:135], v[128:131], v[0:15]
	v_add_u32_e32 v128, v182, v181
	ds_read_b128 v[148:151], v128
	ds_read_b128 v[140:143], v128 offset:2048
	ds_read_b128 v[136:139], v128 offset:4096
	ds_read_b128 v[128:131], v128 offset:6144
	v_add_u32_e32 v132, v183, v181
	ds_read_b128 v[144:147], v132 offset:16384
	ds_read_b128 v[132:135], v132 offset:18432
	s_waitcnt lgkmcnt(6)
	s_add_i32 m0, s8, 0x3000
	s_add_u32 s98, s6, 0x3000
	s_addc_u32 s99, s7, 0
	v_mfma_f32_32x32x16_bf16 v[112:127], v[164:167], v[172:175], v[112:127]
	global_load_lds_dwordx4 v176, s[98:99]
	v_mfma_f32_32x32x16_bf16 v[96:111], v[160:163], v[172:175], v[96:111]
	v_mfma_f32_32x32x16_bf16 v[80:95], v[164:167], v[168:171], v[80:95]
	s_add_i32 m0, s8, 0x4000
	v_mfma_f32_32x32x16_bf16 v[64:79], v[160:163], v[168:171], v[64:79]
	global_load_lds_dwordx4 v176, s[4:5]
	v_mfma_f32_32x32x16_bf16 v[48:63], v[164:167], v[156:159], v[48:63]
	s_add_i32 m0, s8, 0x5000
	s_add_u32 s98, s4, 0x1000
	s_addc_u32 s99, s5, 0
	v_mfma_f32_32x32x16_bf16 v[32:47], v[160:163], v[156:159], v[32:47]
	global_load_lds_dwordx4 v176, s[98:99]
	v_mfma_f32_32x32x16_bf16 v[16:31], v[164:167], v[152:155], v[16:31]
	v_mfma_f32_32x32x16_bf16 v[0:15], v[160:163], v[152:155], v[0:15]
	s_add_u32 s6, s6, 0x80000
	s_addc_u32 s7, s7, 0
	s_add_u32 s4, s4, 0x20000
	s_addc_u32 s5, s5, 0
	s_add_i32 s8, s11, 0x6000
	s_cmpk_lg_u32 s11, 0xc000
	s_cselect_b32 s11, s8, 0
	s_add_i32 s8, s22, 0x6000
	s_cmpk_lg_u32 s22, 0xc000
	s_cselect_b32 s22, s8, 0
	s_add_i32 s1, s1, 1
	s_waitcnt vmcnt(6) lgkmcnt(0)
	s_barrier
	s_cmp_lg_u32 s1, 6
	s_cbranch_scc1 .Lgemm_g4_main
.Lgemm_g4_tail:
	s_setprio 0
	s_add_i32 s33, s22, 0
	v_add_u32_e32 v182, s33, v178
	v_add_u32_e32 v152, v182, v180
	ds_read_b128 v[172:175], v152
	ds_read_b128 v[168:171], v152 offset:2048
	ds_read_b128 v[156:159], v152 offset:4096
	ds_read_b128 v[152:155], v152 offset:6144
	v_add_u32_e32 v183, s33, v179
	v_add_u32_e32 v160, v183, v180
	ds_read_b128 v[164:167], v160 offset:16384
	ds_read_b128 v[160:163], v160 offset:18432
	v_mfma_f32_32x32x16_bf16 v[112:127], v[144:147], v[148:151], v[112:127]
	v_mfma_f32_32x32x16_bf16 v[96:111], v[132:135], v[148:151], v[96:111]
	v_mfma_f32_32x32x16_bf16 v[80:95], v[144:147], v[140:143], v[80:95]
	v_mfma_f32_32x32x16_bf16 v[64:79], v[132:135], v[140:143], v[64:79]
	v_mfma_f32_32x32x16_bf16 v[48:63], v[144:147], v[136:139], v[48:63]
	v_mfma_f32_32x32x16_bf16 v[32:47], v[132:135], v[136:139], v[32:47]
	v_mfma_f32_32x32x16_bf16 v[16:31], v[144:147], v[128:131], v[16:31]
	v_mfma_f32_32x32x16_bf16 v[0:15], v[132:135], v[128:131], v[0:15]
	v_add_u32_e32 v128, v182, v181
	ds_read_b128 v[148:151], v128
	ds_read_b128 v[140:143], v128 offset:2048
	ds_read_b128 v[136:139], v128 offset:4096
	ds_read_b128 v[128:131], v128 offset:6144
	v_add_u32_e32 v132, v183, v181
	ds_read_b128 v[144:147], v132 offset:16384
	ds_read_b128 v[132:135], v132 offset:18432
	s_waitcnt lgkmcnt(6)
	v_mfma_f32_32x32x16_bf16 v[112:127], v[164:167], v[172:175], v[112:127]
	v_mfma_f32_32x32x16_bf16 v[96:111], v[160:163], v[172:175], v[96:111]
	v_mfma_f32_32x32x16_bf16 v[80:95], v[164:167], v[168:171], v[80:95]
	v_mfma_f32_32x32x16_bf16 v[64:79], v[160:163], v[168:171], v[64:79]
	v_mfma_f32_32x32x16_bf16 v[48:63], v[164:167], v[156:159], v[48:63]
	v_mfma_f32_32x32x16_bf16 v[32:47], v[160:163], v[156:159], v[32:47]
	v_mfma_f32_32x32x16_bf16 v[16:31], v[164:167], v[152:155], v[16:31]
	v_mfma_f32_32x32x16_bf16 v[0:15], v[160:163], v[152:155], v[0:15]
	s_add_i32 s8, s22, 0x6000
	s_cmpk_lg_u32 s22, 0xc000
	s_cselect_b32 s22, s8, 0
	s_add_i32 s1, s1, 1
	s_waitcnt vmcnt(0) lgkmcnt(0)
	s_barrier
	s_cmp_lg_u32 s1, 8
	s_cbranch_scc1 .Lgemm_g4_tail
	s_branch .LBB0_311

.LBB0_316:
	s_add_u32 s76, s76, 0x9508000
	s_addc_u32 s77, s77, 0
	s_add_u32 s4, s4, 0x37b0000
	s_addc_u32 s5, s5, 0
	v_mov_b32_e32 v128, 0
	v_mov_b32_e32 v129, 0
	v_mov_b32_e32 v130, 0
	v_mov_b32_e32 v131, 0
	v_mov_b32_e32 v132, 0
	v_mov_b32_e32 v133, 0
	v_mov_b32_e32 v134, 0
	v_mov_b32_e32 v135, 0
	v_mov_b32_e32 v136, 0
	v_mov_b32_e32 v137, 0
	v_mov_b32_e32 v138, 0
	v_mov_b32_e32 v139, 0
	v_mov_b32_e32 v140, 0
	v_mov_b32_e32 v141, 0
	v_mov_b32_e32 v142, 0
	v_mov_b32_e32 v143, 0
	v_mov_b32_e32 v144, 0
	v_mov_b32_e32 v145, 0
	v_mov_b32_e32 v146, 0
	v_mov_b32_e32 v147, 0
	v_mov_b32_e32 v148, 0
	v_mov_b32_e32 v149, 0
	v_mov_b32_e32 v150, 0
	v_mov_b32_e32 v151, 0
	v_readlane_b32 s100, v255, 24
	s_nop 1
	s_bitcmp1_b32 s100, 8
	s_cbranch_scc0 .Lgemm_g5_noyp
	s_setprio 1
.Lgemm_g5_noyp:
.Lgemm_g5_main:
	s_add_i32 s22, s11, 0
	v_add_u32_e32 v183, s22, v179
	v_add_u32_e32 v152, v183, v181
	ds_read_b128 v[172:175], v152
	ds_read_b128 v[168:171], v152 offset:2048
	ds_read_b128 v[156:159], v152 offset:4096
	ds_read_b128 v[152:155], v152 offset:6144
	v_add_u32_e32 v184, s22, v180
	v_add_u32_e32 v160, v184, v181
	ds_read_b128 v[164:167], v160 offset:16384
	ds_read_b128 v[160:163], v160 offset:18432
	s_add_i32 s6, s1, s10
	s_mov_b32 m0, s6
	v_mfma_f32_32x32x16_bf16 v[112:127], v[148:151], v[144:147], v[112:127]
	global_load_lds_dwordx4 v176, s[76:77]
	v_mfma_f32_32x32x16_bf16 v[96:111], v[132:135], v[144:147], v[96:111]
	v_mfma_f32_32x32x16_bf16 v[80:95], v[148:151], v[140:143], v[80:95]
	s_add_i32 m0, s6, 0x1000
	s_add_u32 s98, s76, 0x1000
	s_addc_u32 s99, s77, 0
	v_mfma_f32_32x32x16_bf16 v[64:79], v[132:135], v[140:143], v[64:79]
	global_load_lds_dwordx4 v176, s[98:99]
	v_mfma_f32_32x32x16_bf16 v[48:63], v[148:151], v[136:139], v[48:63]
	s_add_i32 m0, s6, 0x2000
	s_add_u32 s98, s76, 0x2000
	s_addc_u32 s99, s77, 0
	v_mfma_f32_32x32x16_bf16 v[32:47], v[132:135], v[136:139], v[32:47]
	global_load_lds_dwordx4 v176, s[98:99]
	v_mfma_f32_32x32x16_bf16 v[16:31], v[148:151], v[128:131], v[16:31]
	v_mfma_f32_32x32x16_bf16 v[0:15], v[132:135], v[128:131], v[0:15]
	v_add_u32_e32 v128, v183, v182
	ds_read_b128 v[144:147], v128
	ds_read_b128 v[140:143], v128 offset:2048
	ds_read_b128 v[136:139], v128 offset:4096
	ds_read_b128 v[128:131], v128 offset:6144
	v_add_u32_e32 v132, v184, v182
	ds_read_b128 v[148:151], v132 offset:16384
	ds_read_b128 v[132:135], v132 offset:18432
	s_waitcnt lgkmcnt(6)
	s_add_i32 m0, s6, 0x3000
	s_add_u32 s98, s76, 0x3000
	s_addc_u32 s99, s77, 0
	v_mfma_f32_32x32x16_bf16 v[112:127], v[164:167], v[172:175], v[112:127]
	global_load_lds_dwordx4 v176, s[98:99]
	v_mfma_f32_32x32x16_bf16 v[96:111], v[160:163], v[172:175], v[96:111]
	v_mfma_f32_32x32x16_bf16 v[80:95], v[164:167], v[168:171], v[80:95]
	s_add_i32 m0, s6, 0x4000
	v_mfma_f32_32x32x16_bf16 v[64:79], v[160:163], v[168:171], v[64:79]
	global_load_lds_dwordx4 v176, s[4:5]
	v_mfma_f32_32x32x16_bf16 v[48:63], v[164:167], v[156:159], v[48:63]
	s_add_i32 m0, s6, 0x5000
	s_add_u32 s98, s4, 0x1000
	s_addc_u32 s99, s5, 0
	v_mfma_f32_32x32x16_bf16 v[32:47], v[160:163], v[156:159], v[32:47]
	global_load_lds_dwordx4 v176, s[98:99]
	v_mfma_f32_32x32x16_bf16 v[16:31], v[164:167], v[152:155], v[16:31]
	v_mfma_f32_32x32x16_bf16 v[0:15], v[160:163], v[152:155], v[0:15]
	s_add_u32 s76, s76, 0x80000
	s_addc_u32 s77, s77, 0
	s_add_u32 s4, s4, 0x18000
	s_addc_u32 s5, s5, 0
	s_add_i32 s6, s10, 0x6000
	s_cmpk_lg_u32 s10, 0xc000
	s_cselect_b32 s10, s6, 0
	s_add_i32 s6, s11, 0x6000
	s_cmpk_lg_u32 s11, 0xc000
	s_cselect_b32 s11, s6, 0
	s_add_i32 s9, s9, 1
	s_waitcnt vmcnt(6) lgkmcnt(0)
	s_barrier
	s_cmp_lg_u32 s9, 14
	s_cbranch_scc1 .Lgemm_g5_main
.Lgemm_g5_tail:
	s_setprio 0
	s_add_i32 s22, s11, 0
	v_add_u32_e32 v183, s22, v179
	v_add_u32_e32 v152, v183, v181
	ds_read_b128 v[172:175], v152
	ds_read_b128 v[168:171], v152 offset:2048
	ds_read_b128 v[156:159], v152 offset:4096
	ds_read_b128 v[152:155], v152 offset:6144
	v_add_u32_e32 v184, s22, v180
	v_add_u32_e32 v160, v184, v181
	ds_read_b128 v[164:167], v160 offset:16384
	ds_read_b128 v[160:163], v160 offset:18432
	v_mfma_f32_32x32x16_bf16 v[112:127], v[148:151], v[144:147], v[112:127]
	v_mfma_f32_32x32x16_bf16 v[96:111], v[132:135], v[144:147], v[96:111]
	v_mfma_f32_32x32x16_bf16 v[80:95], v[148:151], v[140:143], v[80:95]
	v_mfma_f32_32x32x16_bf16 v[64:79], v[132:135], v[140:143], v[64:79]
	v_mfma_f32_32x32x16_bf16 v[48:63], v[148:151], v[136:139], v[48:63]
	v_mfma_f32_32x32x16_bf16 v[32:47], v[132:135], v[136:139], v[32:47]
	v_mfma_f32_32x32x16_bf16 v[16:31], v[148:151], v[128:131], v[16:31]
	v_mfma_f32_32x32x16_bf16 v[0:15], v[132:135], v[128:131], v[0:15]
	v_add_u32_e32 v128, v183, v182
	ds_read_b128 v[144:147], v128
	ds_read_b128 v[140:143], v128 offset:2048
	ds_read_b128 v[136:139], v128 offset:4096
	ds_read_b128 v[128:131], v128 offset:6144
	v_add_u32_e32 v132, v184, v182
	ds_read_b128 v[148:151], v132 offset:16384
	ds_read_b128 v[132:135], v132 offset:18432
	s_waitcnt lgkmcnt(6)
	v_mfma_f32_32x32x16_bf16 v[112:127], v[164:167], v[172:175], v[112:127]
	v_mfma_f32_32x32x16_bf16 v[96:111], v[160:163], v[172:175], v[96:111]
	v_mfma_f32_32x32x16_bf16 v[80:95], v[164:167], v[168:171], v[80:95]
	v_mfma_f32_32x32x16_bf16 v[64:79], v[160:163], v[168:171], v[64:79]
	v_mfma_f32_32x32x16_bf16 v[48:63], v[164:167], v[156:159], v[48:63]
	v_mfma_f32_32x32x16_bf16 v[32:47], v[160:163], v[156:159], v[32:47]
	v_mfma_f32_32x32x16_bf16 v[16:31], v[164:167], v[152:155], v[16:31]
	v_mfma_f32_32x32x16_bf16 v[0:15], v[160:163], v[152:155], v[0:15]
	s_add_i32 s6, s11, 0x6000
	s_cmpk_lg_u32 s11, 0xc000
	s_cselect_b32 s11, s6, 0
	s_add_i32 s9, s9, 1
	s_waitcnt vmcnt(0) lgkmcnt(0)
	s_barrier
	s_cmp_lg_u32 s9, 16
	s_cbranch_scc1 .Lgemm_g5_tail
	s_branch .LBB0_324

.LBB0_534:
	s_add_u32 s54, s54, s22
	s_addc_u32 s55, s55, s23
	s_add_u32 s50, s50, s44
	s_addc_u32 s51, s51, s45
	v_mov_b32_e32 v128, 0
	v_mov_b32_e32 v129, 0
	v_mov_b32_e32 v130, 0
	v_mov_b32_e32 v131, 0
	v_mov_b32_e32 v132, 0
	v_mov_b32_e32 v133, 0
	v_mov_b32_e32 v134, 0
	v_mov_b32_e32 v135, 0
	v_mov_b32_e32 v136, 0
	v_mov_b32_e32 v137, 0
	v_mov_b32_e32 v138, 0
	v_mov_b32_e32 v139, 0
	v_mov_b32_e32 v140, 0
	v_mov_b32_e32 v141, 0
	v_mov_b32_e32 v142, 0
	v_mov_b32_e32 v143, 0
	v_mov_b32_e32 v144, 0
	v_mov_b32_e32 v145, 0
	v_mov_b32_e32 v146, 0
	v_mov_b32_e32 v147, 0
	v_mov_b32_e32 v148, 0
	v_mov_b32_e32 v149, 0
	v_mov_b32_e32 v150, 0
	v_mov_b32_e32 v151, 0
	v_readlane_b32 s100, v255, 24
	s_nop 1
	s_bitcmp1_b32 s100, 8
	s_cbranch_scc0 .Lgemm_g6_noyp
	s_setprio 1
.Lgemm_g6_noyp:
.Lgemm_g6_main:
	s_add_i32 s58, s76, 0
	v_add_u32_e32 v183, s58, v179
	v_add_u32_e32 v152, v183, v181
	ds_read_b128 v[172:175], v152
	ds_read_b128 v[168:171], v152 offset:2048
	ds_read_b128 v[156:159], v152 offset:4096
	ds_read_b128 v[152:155], v152 offset:6144
	v_add_u32_e32 v184, s58, v180
	v_add_u32_e32 v160, v184, v181
	ds_read_b128 v[164:167], v160 offset:16384
	ds_read_b128 v[160:163], v160 offset:18432
	s_add_i32 s56, s49, s75
	s_mov_b32 m0, s56
	v_mfma_f32_32x32x16_bf16 v[112:127], v[136:139], v[148:151], v[112:127]
	global_load_lds_dwordx4 v176, s[54:55]
	v_mfma_f32_32x32x16_bf16 v[96:111], v[128:131], v[148:151], v[96:111]
	v_mfma_f32_32x32x16_bf16 v[80:95], v[136:139], v[144:147], v[80:95]
	s_add_i32 m0, s56, 0x1000
	s_add_u32 s98, s54, 0x1000
	s_addc_u32 s99, s55, 0
	v_mfma_f32_32x32x16_bf16 v[64:79], v[128:131], v[144:147], v[64:79]
	global_load_lds_dwordx4 v176, s[98:99]
	v_mfma_f32_32x32x16_bf16 v[48:63], v[136:139], v[140:143], v[48:63]
	s_add_i32 m0, s56, 0x2000
	s_add_u32 s98, s54, 0x2000
	s_addc_u32 s99, s55, 0
	v_mfma_f32_32x32x16_bf16 v[32:47], v[128:131], v[140:143], v[32:47]
	global_load_lds_dwordx4 v176, s[98:99]
	v_mfma_f32_32x32x16_bf16 v[16:31], v[136:139], v[132:135], v[16:31]
	v_mfma_f32_32x32x16_bf16 v[0:15], v[128:131], v[132:135], v[0:15]
	v_add_u32_e32 v128, v183, v182
	ds_read_b128 v[148:151], v128
	ds_read_b128 v[144:147], v128 offset:2048
	ds_read_b128 v[140:143], v128 offset:4096
	ds_read_b128 v[132:135], v128 offset:6144
	v_add_u32_e32 v128, v184, v182
	ds_read_b128 v[136:139], v128 offset:16384
	ds_read_b128 v[128:131], v128 offset:18432
	s_waitcnt lgkmcnt(6)
	s_add_i32 m0, s56, 0x3000
	s_add_u32 s98, s54, 0x3000
	s_addc_u32 s99, s55, 0
	v_mfma_f32_32x32x16_bf16 v[112:127], v[164:167], v[172:175], v[112:127]
	global_load_lds_dwordx4 v176, s[98:99]
	v_mfma_f32_32x32x16_bf16 v[96:111], v[160:163], v[172:175], v[96:111]
	v_mfma_f32_32x32x16_bf16 v[80:95], v[164:167], v[168:171], v[80:95]
	s_add_i32 m0, s56, 0x4000
	v_mfma_f32_32x32x16_bf16 v[64:79], v[160:163], v[168:171], v[64:79]
	global_load_lds_dwordx4 v176, s[50:51]
	v_mfma_f32_32x32x16_bf16 v[48:63], v[164:167], v[156:159], v[48:63]
	s_add_i32 m0, s56, 0x5000
	s_add_u32 s98, s50, 0x1000
	s_addc_u32 s99, s51, 0
	v_mfma_f32_32x32x16_bf16 v[32:47], v[160:163], v[156:159], v[32:47]
	global_load_lds_dwordx4 v176, s[98:99]
	v_mfma_f32_32x32x16_bf16 v[16:31], v[164:167], v[152:155], v[16:31]
	v_mfma_f32_32x32x16_bf16 v[0:15], v[160:163], v[152:155], v[0:15]
	s_add_u32 s54, s54, 0x80000
	s_addc_u32 s55, s55, 0
	s_add_u32 s50, s50, 0x20000
	s_addc_u32 s51, s51, 0
	s_add_i32 s56, s75, 0x6000
	s_cmpk_lg_u32 s75, 0xc000
	s_cselect_b32 s75, s56, 0
	s_add_i32 s56, s76, 0x6000
	s_cmpk_lg_u32 s76, 0xc000
	s_cselect_b32 s76, s56, 0
	s_add_i32 s74, s74, 1
	s_waitcnt vmcnt(6) lgkmcnt(0)
	s_barrier
	s_cmp_lg_u32 s74, 62
	s_cbranch_scc1 .Lgemm_g6_main
.Lgemm_g6_tail:
	s_setprio 0
	s_add_i32 s58, s76, 0
	v_add_u32_e32 v183, s58, v179
	v_add_u32_e32 v152, v183, v181
	ds_read_b128 v[172:175], v152
	ds_read_b128 v[168:171], v152 offset:2048
	ds_read_b128 v[156:159], v152 offset:4096
	ds_read_b128 v[152:155], v152 offset:6144
	v_add_u32_e32 v184, s58, v180
	v_add_u32_e32 v160, v184, v181
	ds_read_b128 v[164:167], v160 offset:16384
	ds_read_b128 v[160:163], v160 offset:18432
	v_mfma_f32_32x32x16_bf16 v[112:127], v[136:139], v[148:151], v[112:127]
	v_mfma_f32_32x32x16_bf16 v[96:111], v[128:131], v[148:151], v[96:111]
	v_mfma_f32_32x32x16_bf16 v[80:95], v[136:139], v[144:147], v[80:95]
	v_mfma_f32_32x32x16_bf16 v[64:79], v[128:131], v[144:147], v[64:79]
	v_mfma_f32_32x32x16_bf16 v[48:63], v[136:139], v[140:143], v[48:63]
	v_mfma_f32_32x32x16_bf16 v[32:47], v[128:131], v[140:143], v[32:47]
	v_mfma_f32_32x32x16_bf16 v[16:31], v[136:139], v[132:135], v[16:31]
	v_mfma_f32_32x32x16_bf16 v[0:15], v[128:131], v[132:135], v[0:15]
	v_add_u32_e32 v128, v183, v182
	ds_read_b128 v[148:151], v128
	ds_read_b128 v[144:147], v128 offset:2048
	ds_read_b128 v[140:143], v128 offset:4096
	ds_read_b128 v[132:135], v128 offset:6144
	v_add_u32_e32 v128, v184, v182
	ds_read_b128 v[136:139], v128 offset:16384
	ds_read_b128 v[128:131], v128 offset:18432
	s_waitcnt lgkmcnt(6)
	v_mfma_f32_32x32x16_bf16 v[112:127], v[164:167], v[172:175], v[112:127]
	v_mfma_f32_32x32x16_bf16 v[96:111], v[160:163], v[172:175], v[96:111]
	v_mfma_f32_32x32x16_bf16 v[80:95], v[164:167], v[168:171], v[80:95]
	v_mfma_f32_32x32x16_bf16 v[64:79], v[160:163], v[168:171], v[64:79]
	v_mfma_f32_32x32x16_bf16 v[48:63], v[164:167], v[156:159], v[48:63]
	v_mfma_f32_32x32x16_bf16 v[32:47], v[160:163], v[156:159], v[32:47]
	v_mfma_f32_32x32x16_bf16 v[16:31], v[164:167], v[152:155], v[16:31]
	v_mfma_f32_32x32x16_bf16 v[0:15], v[160:163], v[152:155], v[0:15]
	s_add_i32 s56, s76, 0x6000
	s_cmpk_lg_u32 s76, 0xc000
	s_cselect_b32 s76, s56, 0
	s_add_i32 s74, s74, 1
	s_waitcnt vmcnt(0) lgkmcnt(0)
	s_barrier
	s_cmp_lg_u32 s74, 64
	s_cbranch_scc1 .Lgemm_g6_tail
	s_branch .LBB0_542
